# best_v3 + SO3: hand-written T=(I-A_bb)^-1 back-substitution in the scan (scalar FMAs, row prefetch) replacing hipcc's packed version and its hoisted loads; plus dead address code removed from the S4 h
# speedup vs baseline: 1.0289x; 1.0047x over previous
.LBB0_387:
	s_or_b64 exec, exec, s[16:17]
	v_cndmask_b32_e32 v38, 0, v38, vcc
	v_cndmask_b32_e64 v50, 0, v50, s[10:11]
	v_and_b32_e32 v93, 0xffff0000, v46
	v_lshlrev_b32_e32 v99, 16, v46
	v_and_b32_e32 v46, 0xffff0000, v38
	v_and_b32_e32 v100, 0xffff0000, v50
	v_lshlrev_b32_e32 v38, 16, v38
	v_lshlrev_b32_e32 v50, 16, v50
	v_cndmask_b32_e32 v39, 0, v39, vcc
	v_cndmask_b32_e64 v51, 0, v51, s[10:11]
	v_add_f32_e32 v46, v46, v100
	v_add_f32_e32 v38, v38, v50
	v_fma_f32 v100, v38, 0.5, -v99
	v_fma_f32 v101, v46, 0.5, -v93
	v_and_b32_e32 v38, 0xffff0000, v39
	v_and_b32_e32 v46, 0xffff0000, v51
	v_add_f32_e32 v38, v38, v46
	v_lshlrev_b32_e32 v39, 16, v39
	v_lshlrev_b32_e32 v46, 16, v51
	v_cndmask_b32_e32 v40, 0, v40, vcc
	v_cndmask_b32_e64 v52, 0, v52, s[10:11]
	v_and_b32_e32 v106, 0xffff0000, v47
	v_lshlrev_b32_e32 v127, 16, v47
	v_add_f32_e32 v39, v39, v46
	v_fma_f32 v51, v39, 0.5, -v127
	v_fma_f32 v130, v38, 0.5, -v106
	v_and_b32_e32 v38, 0xffff0000, v40
	v_and_b32_e32 v39, 0xffff0000, v52
	v_add_f32_e32 v46, v97, v98
	v_add_f32_e32 v38, v38, v39
	v_lshlrev_b32_e32 v39, 16, v40
	v_lshlrev_b32_e32 v40, 16, v52
	v_sqrt_f32_e32 v50, v46
	v_cndmask_b32_e32 v41, 0, v41, vcc
	v_cndmask_b32_e64 v53, 0, v53, s[10:11]
	v_and_b32_e32 v131, 0xffff0000, v48
	v_lshlrev_b32_e32 v132, 16, v48
	v_add_f32_e32 v39, v39, v40
	v_fma_f32 v52, v39, 0.5, -v132
	v_fma_f32 v133, v38, 0.5, -v131
	v_and_b32_e32 v38, 0xffff0000, v41
	v_and_b32_e32 v39, 0xffff0000, v53
	v_add_f32_e32 v38, v38, v39
	v_lshlrev_b32_e32 v39, 16, v41
	v_lshlrev_b32_e32 v40, 16, v53
	v_and_b32_e32 v134, 0xffff0000, v49
	v_lshlrev_b32_e32 v135, 16, v49
	v_add_f32_e32 v39, v39, v40
	v_max_f32_e32 v50, 0x2b8cbccc, v50
	v_fma_f32 v53, v39, 0.5, -v135
	v_fma_f32 v136, v38, 0.5, -v134
	v_cvt_f32_f16_sdwa v39, v54 dst_sel:DWORD dst_unused:UNUSED_PAD src0_sel:WORD_1
	v_cvt_f32_f16_e32 v38, v54
	v_cvt_f32_f16_sdwa v41, v55 dst_sel:DWORD dst_unused:UNUSED_PAD src0_sel:WORD_1
	v_cvt_f32_f16_e32 v40, v55
	v_rcp_f32_e32 v50, v50
	v_cvt_f32_f16_sdwa v47, v56 dst_sel:DWORD dst_unused:UNUSED_PAD src0_sel:WORD_1
	v_cvt_f32_f16_e32 v46, v56
	v_cvt_f32_f16_sdwa v49, v57 dst_sel:DWORD dst_unused:UNUSED_PAD src0_sel:WORD_1
	v_cvt_f32_f16_e32 v48, v57
	v_add_u32_e32 v54, v95, v96
	ds_write_b128 v54, v[38:41] offset:34816
	ds_write_b128 v54, v[46:49] offset:34832
	v_pk_mul_f32 v[38:39], v[66:67], v[50:51] op_sel_hi:[1,0]
	v_pk_mul_f32 v[40:41], v[80:81], v[50:51] op_sel_hi:[1,0]
	v_cvt_pk_f16_f32 v38, v38, v39
	v_cvt_pk_f16_f32 v39, v40, v41
	v_pk_mul_f32 v[40:41], v[84:85], v[50:51] op_sel_hi:[1,0]
	v_pk_mul_f32 v[46:47], v[86:87], v[50:51] op_sel_hi:[1,0]
	v_cvt_pk_f16_f32 v40, v40, v41
	v_cvt_pk_f16_f32 v41, v46, v47
	ds_write_b128 v95, v[38:41] offset:51200
	v_pk_mul_f32 v[38:39], v[66:67], v[50:51] op_sel_hi:[1,0] neg_lo:[0,1] neg_hi:[0,1]
	v_pk_mul_f32 v[40:41], v[80:81], v[50:51] op_sel_hi:[1,0] neg_lo:[0,1] neg_hi:[0,1]
	v_pk_mul_f32 v[38:39], v[38:39], v[68:69]
	v_pk_mul_f32 v[40:41], v[40:41], v[78:79]
	v_cvt_pk_f16_f32 v38, v38, v39
	v_cvt_pk_f16_f32 v39, v40, v41
	v_pk_mul_f32 v[40:41], v[84:85], v[50:51] op_sel_hi:[1,0] neg_lo:[0,1] neg_hi:[0,1]
	v_pk_mul_f32 v[46:47], v[86:87], v[50:51] op_sel_hi:[1,0] neg_lo:[0,1] neg_hi:[0,1]
	v_pk_mul_f32 v[40:41], v[40:41], v[82:83]
	v_pk_mul_f32 v[46:47], v[46:47], v[88:89]
	v_cvt_pk_f16_f32 v40, v40, v41
	v_cvt_pk_f16_f32 v41, v46, v47
	ds_write_b128 v95, v[38:41] offset:59392
	v_cvt_pk_f16_f32 v38, v74, v75
	v_cvt_pk_f16_f32 v39, v76, v77
	v_cvt_pk_f16_f32 v40, v72, v73
	v_cvt_pk_f16_f32 v41, v70, v71
	v_add_u32_e32 v46, 0x10800, v95
	ds_write_b128 v46, v[38:41]
	v_cvt_pk_f16_f32 v38, v58, v59
	v_cvt_pk_f16_f32 v39, v60, v61
	v_cvt_pk_f16_f32 v40, v62, v63
	v_cvt_pk_f16_f32 v41, v64, v65
	v_add_u32_e32 v46, 0x12800, v95
	ds_write_b128 v46, v[38:41]
	v_lshlrev_b32_e32 v38, 7, v94
	v_lshlrev_b32_e32 v39, 8, v91
	v_and_b32_e32 v38, 0xfffff800, v38
	s_add_i32 s10, 0, 0x18800
	v_and_b32_e32 v39, 0x400, v39
	v_lshlrev_b32_e32 v40, 8, v90
	v_add3_u32 v38, s10, v38, v39
	v_lshlrev_b32_e32 v39, 2, v92
	v_and_b32_e32 v40, 0x300, v40
	v_and_b32_e32 v39, 16, v39
	v_add3_u32 v38, v38, v40, v39
	v_lshlrev_b32_e32 v39, 1, v92
	v_and_b32_e32 v39, 6, v39
	v_and_b32_e32 v40, 8, v94
	v_add3_u32 v38, v38, v40, v39
	v_fma_mixlo_f16 v34, v34, v52, v132
	v_fma_mixlo_f16 v39, v42, v100, v99
	ds_write_b16 v38, v34 offset:128
	v_fma_mixlo_f16 v34, v35, v133, v131
	ds_write_b16 v38, v39
	v_fma_mixlo_f16 v39, v43, v101, v93
	ds_write_b16 v38, v34 offset:160
	v_fma_mixlo_f16 v34, v36, v53, v135
	ds_write_b16 v38, v39 offset:32
	v_fma_mixlo_f16 v39, v44, v51, v127
	ds_write_b16 v38, v34 offset:192
	v_fma_mixlo_f16 v34, v136, v37, v134
	v_lshlrev_b32_e32 v44, 2, v90
	ds_write_b16 v38, v39 offset:64
	v_fma_mixlo_f16 v39, v45, v130, v106
	ds_write_b16 v38, v34 offset:224
	v_lshlrev_b32_e32 v34, 1, v90
	v_add_u32_e32 v43, s75, v44
	ds_write_b16 v38, v39 offset:96
	s_waitcnt lgkmcnt(0)
	s_barrier
	v_and_b32_e32 v46, 6, v34
	ds_read2st64_b32 v[34:35], v43 offset0:136 offset1:137
	ds_read2st64_b32 v[36:37], v43 offset0:138 offset1:139
	ds_read2st64_b32 v[38:39], v43 offset0:140 offset1:141
	ds_read2st64_b32 v[40:41], v43 offset0:142 offset1:143
	v_ashrrev_i32_e32 v42, 4, v90
	v_and_b32_e32 v48, 8, v90
	s_movk_i32 s14, 0x3c0
	s_waitcnt lgkmcnt(3)
	v_add_f32_e32 v68, 0, v34
	v_add_f32_e32 v65, v68, v35
	s_waitcnt lgkmcnt(2)
	v_add_f32_e32 v63, v65, v36
	v_add_f32_e32 v61, v63, v37
	ds_read2st64_b32 v[34:35], v43 offset0:144 offset1:145
	s_waitcnt lgkmcnt(2)
	v_add_f32_e32 v59, v61, v38
	v_add_f32_e32 v57, v59, v39
	s_waitcnt lgkmcnt(1)
	v_add_f32_e32 v53, v57, v40
	v_add_f32_e32 v36, v53, v41
	ds_read2st64_b32 v[38:39], v43 offset0:146 offset1:147
	ds_read2st64_b32 v[40:41], v43 offset0:148 offset1:149
	ds_read2st64_b32 v[54:55], v43 offset0:150 offset1:151
	s_waitcnt lgkmcnt(3)
	v_add_f32_e32 v51, v36, v34
	v_add_f32_e32 v49, v51, v35
	s_waitcnt lgkmcnt(2)
	v_add_f32_e32 v47, v49, v38
	v_add_f32_e32 v45, v47, v39
	s_waitcnt lgkmcnt(1)
	v_add_f32_e32 v43, v45, v40
	v_add_f32_e32 v41, v43, v41
	v_and_b32_e32 v34, 16, v44
	s_waitcnt lgkmcnt(0)
	v_add_f32_e32 v39, v41, v54
	v_or3_b32 v34, v46, v48, v34
	v_lshlrev_b32_e32 v35, 10, v42
	v_add_u32_e32 v37, s77, v90
	v_lshlrev_b32_e32 v38, 6, v42
	v_and_b32_e32 v128, 31, v90
	v_ashrrev_i32_e32 v125, 5, v90
	v_add_f32_e32 v66, v39, v55
	s_mov_b64 s[10:11], -1
	s_and_b64 vcc, exec, s[88:89]
	v_add3_u32 v34, s75, v35, v34
	v_lshl_add_u32 v37, v37, 1, 0
	s_cbranch_vccz .LBB0_389
	s_movk_i32 s32, 0x3e0
	v_add_u32_e32 v48, 0x10800, v37
	v_add_u32_e32 v50, v34, v38
	ds_read_u16 v69, v37 offset:59392
	ds_read_u16 v70, v48 offset:0
	ds_read_u16 v71, v37 offset:59520
	ds_read_u16 v72, v48 offset:128
	ds_read_u16 v73, v37 offset:59648
	ds_read_u16 v74, v48 offset:256
	ds_read_u16 v75, v37 offset:59776
	ds_read_u16 v76, v48 offset:384
	ds_read_u16 v77, v37 offset:59904
	ds_read_u16 v78, v48 offset:512
	ds_read_u16 v79, v37 offset:60032
	ds_read_u16 v88, v48 offset:640
	v_sub_f32_e32 v52, v36, v68
	v_mul_f32_e32 v52, 0x3fb8aa3b, v52
	v_exp_f32_e32 v52, v52
	ds_read_u16 v89, v37 offset:60160
	ds_read_u16 v91, v48 offset:768
	s_waitcnt lgkmcnt(13)
	v_fma_mix_f32 v40, v52, v69, 0 op_sel_hi:[0,1,0]
	s_waitcnt lgkmcnt(12)
	v_fma_mix_f32 v44, v52, v70, 0 op_sel_hi:[0,1,0]
	v_sub_f32_e32 v54, v36, v65
	v_mul_f32_e32 v54, 0x3fb8aa3b, v54
	v_exp_f32_e32 v54, v54
	ds_read_u16 v100, v37 offset:60288
	ds_read_u16 v101, v48 offset:896
	s_waitcnt lgkmcnt(13)
	v_fma_mix_f32 v42, v54, v71, 0 op_sel_hi:[0,1,0]
	s_waitcnt lgkmcnt(12)
	v_fma_mix_f32 v46, v54, v72, 0 op_sel_hi:[0,1,0]
	v_cvt_pk_f16_f32 v92, v40, v42
	v_cvt_pk_f16_f32 v80, v44, v46
	ds_write_b16 v50, v92 offset:16384
	ds_write_b16_d16_hi v50, v92 offset:16416
	s_waitcnt lgkmcnt(8)
	ds_write_b16 v50, v80 offset:16896
	ds_write_b16_d16_hi v50, v80 offset:16928
	v_sub_f32_e32 v52, v36, v63
	v_mul_f32_e32 v52, 0x3fb8aa3b, v52
	v_exp_f32_e32 v52, v52
	ds_read_u16 v69, v37 offset:60416
	ds_read_u16 v70, v48 offset:1024
	v_fma_mix_f32 v40, v52, v73, 0 op_sel_hi:[0,1,0]
	v_fma_mix_f32 v44, v52, v74, 0 op_sel_hi:[0,1,0]
	v_sub_f32_e32 v54, v36, v61
	v_mul_f32_e32 v54, 0x3fb8aa3b, v54
	v_exp_f32_e32 v54, v54
	ds_read_u16 v71, v37 offset:60544
	ds_read_u16 v72, v48 offset:1152
	v_fma_mix_f32 v42, v54, v75, 0 op_sel_hi:[0,1,0]
	v_fma_mix_f32 v46, v54, v76, 0 op_sel_hi:[0,1,0]
	v_cvt_pk_f16_f32 v93, v40, v42
	v_cvt_pk_f16_f32 v81, v44, v46
	s_waitcnt lgkmcnt(8)
	ds_write_b16 v50, v93 offset:16448
	ds_write_b16_d16_hi v50, v93 offset:16480
	ds_write_b16 v50, v81 offset:16960
	ds_write_b16_d16_hi v50, v81 offset:16992
	v_sub_f32_e32 v52, v36, v59
	v_mul_f32_e32 v52, 0x3fb8aa3b, v52
	v_exp_f32_e32 v52, v52
	ds_read_u16 v73, v37 offset:60672
	ds_read_u16 v74, v48 offset:1280
	v_fma_mix_f32 v40, v52, v77, 0 op_sel_hi:[0,1,0]
	v_fma_mix_f32 v44, v52, v78, 0 op_sel_hi:[0,1,0]
	v_sub_f32_e32 v54, v36, v57
	v_mul_f32_e32 v54, 0x3fb8aa3b, v54
	v_exp_f32_e32 v54, v54
	s_waitcnt lgkmcnt(8)
	ds_read_u16 v75, v37 offset:60800
	ds_read_u16 v76, v48 offset:1408
	v_fma_mix_f32 v42, v54, v79, 0 op_sel_hi:[0,1,0]
	v_fma_mix_f32 v46, v54, v88, 0 op_sel_hi:[0,1,0]
	v_cvt_pk_f16_f32 v96, v40, v42
	v_cvt_pk_f16_f32 v84, v44, v46
	ds_write_b16 v50, v96 offset:16512
	ds_write_b16_d16_hi v50, v96 offset:16544
	ds_write_b16 v50, v84 offset:17024
	ds_write_b16_d16_hi v50, v84 offset:17056
	v_sub_f32_e32 v52, v36, v53
	v_mul_f32_e32 v52, 0x3fb8aa3b, v52
	v_exp_f32_e32 v52, v52
	s_waitcnt lgkmcnt(8)
	ds_read_u16 v77, v37 offset:60928
	ds_read_u16 v78, v48 offset:1536
	v_fma_mix_f32 v40, v52, v89, 0 op_sel_hi:[0,1,0]
	v_fma_mix_f32 v44, v52, v91, 0 op_sel_hi:[0,1,0]
	v_cvt_f32_f16_e32 v42, v100
	v_cvt_f32_f16_e32 v46, v101
	ds_read_u16 v79, v37 offset:61056
	ds_read_u16 v88, v48 offset:1664
	v_cvt_pk_f16_f32 v97, v40, v42
	v_cvt_pk_f16_f32 v85, v44, v46
	ds_write_b16 v50, v97 offset:16576
	ds_write_b16_d16_hi v50, v97 offset:16608
	s_waitcnt lgkmcnt(8)
	ds_write_b16 v50, v85 offset:17088
	ds_write_b16_d16_hi v50, v85 offset:17120
	v_sub_f32_e32 v52, v36, v51
	v_mul_f32_e32 v52, 0x3fb8aa3b, v52
	v_exp_f32_e32 v52, v52
	ds_read_u16 v89, v37 offset:61184
	ds_read_u16 v91, v48 offset:1792
	v_fma_mix_f32 v40, v52, v69, 0 op_sel_hi:[0,1,0]
	v_fma_mix_f32 v44, v52, v70, 0 op_sel_hi:[0,1,0]
	v_sub_f32_e32 v54, v36, v49
	v_mul_f32_e32 v54, 0x3fb8aa3b, v54
	v_exp_f32_e32 v54, v54
	ds_read_u16 v100, v37 offset:61312
	ds_read_u16 v101, v48 offset:1920
	v_fma_mix_f32 v42, v54, v71, 0 op_sel_hi:[0,1,0]
	v_fma_mix_f32 v46, v54, v72, 0 op_sel_hi:[0,1,0]
	v_cvt_pk_f16_f32 v94, v40, v42
	v_cvt_pk_f16_f32 v82, v44, v46
	s_waitcnt lgkmcnt(8)
	ds_write_b16 v50, v94 offset:16640
	ds_write_b16_d16_hi v50, v94 offset:16672
	ds_write_b16 v50, v82 offset:17152
	ds_write_b16_d16_hi v50, v82 offset:17184
	v_sub_f32_e32 v52, v36, v47
	v_mul_f32_e32 v52, 0x3fb8aa3b, v52
	v_exp_f32_e32 v52, v52
	s_nop 0
	v_fma_mix_f32 v40, v52, v73, 0 op_sel_hi:[0,1,0]
	v_fma_mix_f32 v44, v52, v74, 0 op_sel_hi:[0,1,0]
	v_sub_f32_e32 v54, v36, v45
	v_mul_f32_e32 v54, 0x3fb8aa3b, v54
	v_exp_f32_e32 v54, v54
	s_nop 0
	v_fma_mix_f32 v42, v54, v75, 0 op_sel_hi:[0,1,0]
	v_fma_mix_f32 v46, v54, v76, 0 op_sel_hi:[0,1,0]
	v_cvt_pk_f16_f32 v95, v40, v42
	v_cvt_pk_f16_f32 v83, v44, v46
	ds_write_b16 v50, v95 offset:16704
	ds_write_b16_d16_hi v50, v95 offset:16736
	v_add_u32_e32 v56, 0x340, v38
	v_and_or_b32 v56, v56, s32, v34
	s_waitcnt lgkmcnt(8)
	ds_write_b16 v56, v83 offset:16384
	ds_write_b16_d16_hi v56, v83 offset:16416
	v_sub_f32_e32 v52, v36, v43
	v_mul_f32_e32 v52, 0x3fb8aa3b, v52
	v_exp_f32_e32 v52, v52
	s_nop 0
	v_fma_mix_f32 v40, v52, v77, 0 op_sel_hi:[0,1,0]
	v_fma_mix_f32 v44, v52, v78, 0 op_sel_hi:[0,1,0]
	v_sub_f32_e32 v54, v36, v41
	v_mul_f32_e32 v54, 0x3fb8aa3b, v54
	v_exp_f32_e32 v54, v54
	s_nop 0
	v_fma_mix_f32 v42, v54, v79, 0 op_sel_hi:[0,1,0]
	v_fma_mix_f32 v46, v54, v88, 0 op_sel_hi:[0,1,0]
	v_cvt_pk_f16_f32 v98, v40, v42
	v_cvt_pk_f16_f32 v86, v44, v46
	ds_write_b16 v50, v98 offset:16768
	ds_write_b16_d16_hi v50, v98 offset:16800
	v_add_u32_e32 v56, 0x380, v38
	v_and_or_b32 v56, v56, s32, v34
	ds_write_b16 v56, v86 offset:16384
	ds_write_b16_d16_hi v56, v86 offset:16416
	v_sub_f32_e32 v52, v36, v39
	v_mul_f32_e32 v52, 0x3fb8aa3b, v52
	v_exp_f32_e32 v52, v52
	s_nop 0
	v_fma_mix_f32 v40, v52, v89, 0 op_sel_hi:[0,1,0]
	v_fma_mix_f32 v44, v52, v91, 0 op_sel_hi:[0,1,0]
	v_sub_f32_e32 v54, v36, v66
	v_mul_f32_e32 v54, 0x3fb8aa3b, v54
	v_exp_f32_e32 v54, v54
	s_waitcnt lgkmcnt(13)
	v_fma_mix_f32 v42, v54, v100, 0 op_sel_hi:[0,1,0]
	s_waitcnt lgkmcnt(12)
	v_fma_mix_f32 v46, v54, v101, 0 op_sel_hi:[0,1,0]
	v_cvt_pk_f16_f32 v99, v40, v42
	v_cvt_pk_f16_f32 v87, v44, v46
	ds_write_b16 v50, v99 offset:16832
	ds_write_b16_d16_hi v50, v99 offset:16864
	v_add_u32_e32 v56, 0x3c0, v38
	v_and_or_b32 v56, v56, s32, v34
	s_waitcnt lgkmcnt(8)
	ds_write_b16 v56, v87 offset:16384
	ds_write_b16_d16_hi v56, v87 offset:16416
	v_lshlrev_b32_e32 v58, 11, v125
	v_lshlrev_b32_e32 v60, 5, v128
	v_add3_u32 v58, s76, v58, v60
	ds_write_b128 v58, v[92:95]
	ds_write_b128 v58, v[96:99] offset:16
	ds_write_b128 v58, v[80:83] offset:1024
	ds_write_b128 v58, v[84:87] offset:1040
	s_mov_b64 s[10:11], 0
.LBB0_389:
	s_andn2_b64 vcc, exec, s[10:11]
	s_cbranch_vccnz .LBB0_391
	s_movk_i32 s32, 0x3e0
	v_add_u32_e32 v48, 0x12800, v37
	v_add_u32_e32 v50, v34, v38
	ds_read_u16 v69, v37 offset:51200
	ds_read_u16 v70, v48 offset:0
	ds_read_u16 v71, v37 offset:51328
	ds_read_u16 v72, v48 offset:128
	ds_read_u16 v73, v37 offset:51456
	ds_read_u16 v74, v48 offset:256
	ds_read_u16 v75, v37 offset:51584
	ds_read_u16 v76, v48 offset:384
	ds_read_u16 v77, v37 offset:51712
	ds_read_u16 v78, v48 offset:512
	ds_read_u16 v79, v37 offset:51840
	ds_read_u16 v88, v48 offset:640
	v_mul_f32_e32 v84, 0xbfb8aa3b, v36
	v_exp_f32_e32 v84, v84
	v_mul_f32_e32 v85, 0x3fb8aa3b, v36
	v_exp_f32_e32 v85, v85
	v_sub_f32_e32 v80, v68, v36
	v_mul_f32_e32 v80, 0x3fb8aa3b, v80
	v_exp_f32_e32 v80, v80
	ds_read_u16 v89, v37 offset:51968
	ds_read_u16 v91, v48 offset:768
	s_waitcnt lgkmcnt(13)
	v_fma_mixlo_f16 v40, v84, v69, 0 op_sel_hi:[0,1,0]
	s_waitcnt lgkmcnt(12)
	v_fma_mixlo_f16 v42, v80, v70, 0 op_sel_hi:[0,1,0]
	ds_write_b16 v50, v40 offset:0
	ds_write_b16 v50, v42 offset:512
	v_sub_f32_e32 v81, v65, v36
	v_mul_f32_e32 v81, 0x3fb8aa3b, v81
	v_exp_f32_e32 v81, v81
	s_waitcnt lgkmcnt(8)
	ds_read_u16 v100, v37 offset:52096
	ds_read_u16 v101, v48 offset:896
	v_fma_mixlo_f16 v44, v80, v71, 0 op_sel_hi:[0,1,0]
	v_fma_mixlo_f16 v46, v81, v72, 0 op_sel_hi:[0,1,0]
	ds_write_b16 v50, v44 offset:32
	ds_write_b16 v50, v46 offset:544
	v_sub_f32_e32 v82, v63, v36
	v_mul_f32_e32 v82, 0x3fb8aa3b, v82
	v_exp_f32_e32 v82, v82
	ds_read_u16 v69, v37 offset:52224
	ds_read_u16 v70, v48 offset:1024
	v_fma_mixlo_f16 v40, v81, v73, 0 op_sel_hi:[0,1,0]
	v_fma_mixlo_f16 v42, v82, v74, 0 op_sel_hi:[0,1,0]
	s_waitcnt lgkmcnt(8)
	ds_write_b16 v50, v40 offset:64
	ds_write_b16 v50, v42 offset:576
	v_sub_f32_e32 v83, v61, v36
	v_mul_f32_e32 v83, 0x3fb8aa3b, v83
	v_exp_f32_e32 v83, v83
	ds_read_u16 v71, v37 offset:52352
	ds_read_u16 v72, v48 offset:1152
	v_fma_mixlo_f16 v44, v82, v75, 0 op_sel_hi:[0,1,0]
	v_fma_mixlo_f16 v46, v83, v76, 0 op_sel_hi:[0,1,0]
	ds_write_b16 v50, v44 offset:96
	ds_write_b16 v50, v46 offset:608
	v_sub_f32_e32 v80, v59, v36
	v_mul_f32_e32 v80, 0x3fb8aa3b, v80
	v_exp_f32_e32 v80, v80
	s_waitcnt lgkmcnt(8)
	ds_read_u16 v73, v37 offset:52480
	ds_read_u16 v74, v48 offset:1280
	v_fma_mixlo_f16 v40, v83, v77, 0 op_sel_hi:[0,1,0]
	v_fma_mixlo_f16 v42, v80, v78, 0 op_sel_hi:[0,1,0]
	ds_write_b16 v50, v40 offset:128
	ds_write_b16 v50, v42 offset:640
	v_sub_f32_e32 v81, v57, v36
	v_mul_f32_e32 v81, 0x3fb8aa3b, v81
	v_exp_f32_e32 v81, v81
	ds_read_u16 v75, v37 offset:52608
	ds_read_u16 v76, v48 offset:1408
	v_fma_mixlo_f16 v44, v80, v79, 0 op_sel_hi:[0,1,0]
	v_fma_mixlo_f16 v46, v81, v88, 0 op_sel_hi:[0,1,0]
	s_waitcnt lgkmcnt(8)
	ds_write_b16 v50, v44 offset:160
	ds_write_b16 v50, v46 offset:672
	v_sub_f32_e32 v82, v53, v36
	v_mul_f32_e32 v82, 0x3fb8aa3b, v82
	v_exp_f32_e32 v82, v82
	ds_read_u16 v77, v37 offset:52736
	ds_read_u16 v78, v48 offset:1536
	v_fma_mixlo_f16 v40, v81, v89, 0 op_sel_hi:[0,1,0]
	v_fma_mixlo_f16 v42, v82, v91, 0 op_sel_hi:[0,1,0]
	ds_write_b16 v50, v40 offset:192
	ds_write_b16 v50, v42 offset:704
	v_mov_b32_e32 v83, 1.0
	s_waitcnt lgkmcnt(8)
	ds_read_u16 v79, v37 offset:52864
	ds_read_u16 v88, v48 offset:1664
	v_fma_mixlo_f16 v44, v82, v100, 0 op_sel_hi:[0,1,0]
	v_fma_mixlo_f16 v46, v83, v101, 0 op_sel_hi:[0,1,0]
	ds_write_b16 v50, v44 offset:224
	ds_write_b16 v50, v46 offset:736
	v_sub_f32_e32 v80, v51, v36
	v_mul_f32_e32 v80, 0x3fb8aa3b, v80
	v_exp_f32_e32 v80, v80
	ds_read_u16 v89, v37 offset:52992
	ds_read_u16 v91, v48 offset:1792
	v_fma_mixlo_f16 v40, v83, v69, 0 op_sel_hi:[0,1,0]
	v_fma_mixlo_f16 v42, v80, v70, 0 op_sel_hi:[0,1,0]
	s_waitcnt lgkmcnt(8)
	ds_write_b16 v50, v40 offset:256
	ds_write_b16 v50, v42 offset:768
	v_sub_f32_e32 v81, v49, v36
	v_mul_f32_e32 v81, 0x3fb8aa3b, v81
	v_exp_f32_e32 v81, v81
	ds_read_u16 v100, v37 offset:53120
	ds_read_u16 v101, v48 offset:1920
	v_fma_mixlo_f16 v44, v80, v71, 0 op_sel_hi:[0,1,0]
	v_fma_mixlo_f16 v46, v81, v72, 0 op_sel_hi:[0,1,0]
	ds_write_b16 v50, v44 offset:288
	ds_write_b16 v50, v46 offset:800
	v_sub_f32_e32 v82, v47, v36
	v_mul_f32_e32 v82, 0x3fb8aa3b, v82
	v_exp_f32_e32 v82, v82
	v_fma_mixlo_f16 v40, v81, v73, 0 op_sel_hi:[0,1,0]
	v_fma_mixlo_f16 v42, v82, v74, 0 op_sel_hi:[0,1,0]
	s_waitcnt lgkmcnt(8)
	ds_write_b16 v50, v40 offset:320
	v_add_u32_e32 v56, 0x340, v38
	v_and_or_b32 v56, v56, s32, v34
	ds_write_b16 v56, v42
	v_sub_f32_e32 v83, v45, v36
	v_mul_f32_e32 v83, 0x3fb8aa3b, v83
	v_exp_f32_e32 v83, v83
	v_fma_mixlo_f16 v44, v82, v75, 0 op_sel_hi:[0,1,0]
	v_fma_mixlo_f16 v46, v83, v76, 0 op_sel_hi:[0,1,0]
	ds_write_b16 v50, v44 offset:352
	ds_write_b16 v56, v46 offset:32
	v_sub_f32_e32 v80, v43, v36
	v_mul_f32_e32 v80, 0x3fb8aa3b, v80
	v_exp_f32_e32 v80, v80
	v_fma_mixlo_f16 v40, v83, v77, 0 op_sel_hi:[0,1,0]
	v_fma_mixlo_f16 v42, v80, v78, 0 op_sel_hi:[0,1,0]
	ds_write_b16 v50, v40 offset:384
	v_add_u32_e32 v56, 0x380, v38
	v_and_or_b32 v56, v56, s32, v34
	ds_write_b16 v56, v42
	v_sub_f32_e32 v81, v41, v36
	v_mul_f32_e32 v81, 0x3fb8aa3b, v81
	v_exp_f32_e32 v81, v81
	v_fma_mixlo_f16 v44, v80, v79, 0 op_sel_hi:[0,1,0]
	v_fma_mixlo_f16 v46, v81, v88, 0 op_sel_hi:[0,1,0]
	s_waitcnt lgkmcnt(8)
	ds_write_b16 v50, v44 offset:416
	ds_write_b16 v56, v46 offset:32
	v_sub_f32_e32 v82, v39, v36
	v_mul_f32_e32 v82, 0x3fb8aa3b, v82
	v_exp_f32_e32 v82, v82
	v_fma_mixlo_f16 v40, v81, v89, 0 op_sel_hi:[0,1,0]
	v_fma_mixlo_f16 v42, v82, v91, 0 op_sel_hi:[0,1,0]
	ds_write_b16 v50, v40 offset:448
	v_add_u32_e32 v56, 0x3c0, v38
	v_and_or_b32 v56, v56, s32, v34
	ds_write_b16 v56, v42
	v_sub_f32_e32 v83, v66, v36
	v_mul_f32_e32 v83, 0x3fb8aa3b, v83
	v_exp_f32_e32 v83, v83
	v_fma_mixlo_f16 v44, v82, v100, 0 op_sel_hi:[0,1,0]
	v_fma_mixlo_f16 v46, v83, v101, 0 op_sel_hi:[0,1,0]
	ds_write_b16 v50, v44 offset:480
	ds_write_b16 v56, v46 offset:32
	v_lshl_add_u32 v58, v90, 2, s62
	s_waitcnt lgkmcnt(8)
	ds_write2st64_b32 v58, v85, v83 offset1:1

.LBB0_429:
	s_or_b64 exec, exec, s[10:11]
	v_add_u32_e32 v46, s51, v50
	ds_write_b128 v46, v[42:45]
	v_add_u32_e32 v42, s5, v50
	ds_write_b128 v42, v[34:37]
	ds_write_b128 v42, v[38:41] offset:1024
	s_waitcnt lgkmcnt(0)
	v_cmp_lt_i32_e32 vcc, 15, v90
	s_and_saveexec_b64 s[10:11], vcc
	s_xor_b64 s[10:11], exec, s[10:11]
	s_cbranch_execz .LBB0_433
	v_cmp_gt_u32_e32 vcc, 32, v90
	s_and_saveexec_b64 s[14:15], vcc
	s_cbranch_execz .LBB0_432
	s_mov_b32 s40, s41
	s_waitcnt lgkmcnt(11)
	v_add_u32_e32 v34, s42, v216
	s_mov_b32 s16, s42
	s_mov_b32 s42, s41
	s_mov_b32 s43, s41
	s_waitcnt lgkmcnt(8)
	v_mov_b64_e32 v[36:37], s[40:41]
	v_mov_b64_e32 v[38:39], s[42:43]
	s_mov_b32 s42, s16
	ds_write_b128 v34, v[36:39]
	ds_write_b128 v34, v[36:39] offset:16

.LBB0_433:
	s_andn2_saveexec_b64 s[10:11], s[10:11]
	s_cbranch_execz .LBB0_435
	v_mov_b32_e32 v62, s44
	v_and_b32_e32 v63, 15, v90
	ds_read_b128 v[188:191], v62 offset:944
	ds_read_b128 v[192:195], v62 offset:880
	ds_read_b128 v[196:199], v62 offset:816
	ds_read_b128 v[220:223], v62 offset:752
	ds_read_b128 v[76:79], v62 offset:672
	ds_read_b128 v[96:99], v62 offset:688
	ds_read_b128 v[64:67], v62 offset:608
	ds_read_b128 v[160:163], v62 offset:624
	v_cmp_eq_u32_e32 vcc, 15, v63
	v_add_u32_e32 v68, s42, v216
	s_nop 0
	v_cndmask_b32_e64 v183, 0, 1.0, vcc
	v_cmp_eq_u32_e32 vcc, 14, v63
	s_waitcnt lgkmcnt(7)
	s_nop 0
	v_cndmask_b32_e64 v184, 0, 1.0, vcc
	v_mul_f32_e32 v187, v191, v183
	v_cmp_eq_u32_e32 vcc, 13, v63
	v_add_f32_e32 v182, v184, v187
	s_waitcnt lgkmcnt(6)
	v_cndmask_b32_e64 v184, 0, 1.0, vcc
	v_mul_f32_e32 v186, v194, v182
	v_mul_f32_e32 v187, v195, v183
	v_cmp_eq_u32_e32 vcc, 12, v63
	ds_read_b128 v[188:191], v62 offset:544
	ds_read_b128 v[192:195], v62 offset:560
	v_add_f32_e32 v186, v186, v187
	v_add_f32_e32 v181, v184, v186
	s_waitcnt lgkmcnt(7)
	v_cndmask_b32_e64 v184, 0, 1.0, vcc
	v_mul_f32_e32 v185, v197, v181
	v_mul_f32_e32 v186, v198, v182
	v_mul_f32_e32 v187, v199, v183
	v_cmp_eq_u32_e32 vcc, 11, v63
	v_add_f32_e32 v184, v184, v185
	v_add_f32_e32 v186, v186, v187
	v_add_f32_e32 v180, v184, v186
	s_waitcnt lgkmcnt(6)
	v_cndmask_b32_e64 v184, 0, 1.0, vcc
	v_fmac_f32_e32 v184, v220, v180
	v_mul_f32_e32 v185, v221, v181
	v_mul_f32_e32 v186, v222, v182
	v_mul_f32_e32 v187, v223, v183
	v_cmp_eq_u32_e32 vcc, 10, v63
	ds_read_b128 v[196:199], v62 offset:480
	ds_read_b128 v[220:223], v62 offset:496
	v_add_f32_e32 v184, v184, v185
	v_add_f32_e32 v186, v186, v187
	v_add_f32_e32 v179, v184, v186
	s_waitcnt lgkmcnt(6)
	v_cndmask_b32_e64 v184, 0, 1.0, vcc
	v_mul_f32_e32 v187, v79, v179
	v_fmac_f32_e32 v184, v96, v180
	v_mul_f32_e32 v185, v97, v181
	v_mul_f32_e32 v186, v98, v182
	v_fmac_f32_e32 v187, v99, v183
	v_cmp_eq_u32_e32 vcc, 9, v63
	v_add_f32_e32 v184, v184, v185
	v_add_f32_e32 v186, v186, v187
	v_add_f32_e32 v178, v184, v186
	s_waitcnt lgkmcnt(4)
	v_cndmask_b32_e64 v184, 0, 1.0, vcc
	v_mul_f32_e32 v186, v66, v178
	v_mul_f32_e32 v187, v67, v179
	v_fmac_f32_e32 v184, v160, v180
	v_mul_f32_e32 v185, v161, v181
	v_fmac_f32_e32 v186, v162, v182
	v_fmac_f32_e32 v187, v163, v183
	v_cmp_eq_u32_e32 vcc, 8, v63
	ds_read_b128 v[76:79], v62 offset:400
	ds_read_b128 v[96:99], v62 offset:416
	ds_read_b128 v[64:67], v62 offset:432
	v_add_f32_e32 v184, v184, v185
	v_add_f32_e32 v186, v186, v187
	v_add_f32_e32 v177, v184, v186
	s_waitcnt lgkmcnt(5)
	v_cndmask_b32_e64 v184, 0, 1.0, vcc
	v_mul_f32_e32 v185, v189, v177
	v_mul_f32_e32 v186, v190, v178
	v_mul_f32_e32 v187, v191, v179
	v_fmac_f32_e32 v184, v192, v180
	v_fmac_f32_e32 v185, v193, v181
	v_fmac_f32_e32 v186, v194, v182
	v_fmac_f32_e32 v187, v195, v183
	v_cmp_eq_u32_e32 vcc, 7, v63
	ds_read_b128 v[160:163], v62 offset:336
	ds_read_b128 v[188:191], v62 offset:352
	ds_read_b128 v[192:195], v62 offset:368
	v_add_f32_e32 v184, v184, v185
	v_add_f32_e32 v186, v186, v187
	v_add_f32_e32 v176, v184, v186
	s_waitcnt lgkmcnt(6)
	v_cndmask_b32_e64 v184, 0, 1.0, vcc
	v_fmac_f32_e32 v184, v196, v176
	v_mul_f32_e32 v185, v197, v177
	v_mul_f32_e32 v186, v198, v178
	v_mul_f32_e32 v187, v199, v179
	v_fmac_f32_e32 v184, v220, v180
	v_fmac_f32_e32 v185, v221, v181
	v_fmac_f32_e32 v186, v222, v182
	v_fmac_f32_e32 v187, v223, v183
	v_cmp_eq_u32_e32 vcc, 6, v63
	v_add_f32_e32 v184, v184, v185
	v_add_f32_e32 v186, v186, v187
	v_add_f32_e32 v175, v184, v186
	s_waitcnt lgkmcnt(3)
	v_cndmask_b32_e64 v184, 0, 1.0, vcc
	v_mul_f32_e32 v187, v79, v175
	v_fmac_f32_e32 v184, v96, v176
	v_mul_f32_e32 v185, v97, v177
	v_mul_f32_e32 v186, v98, v178
	v_fmac_f32_e32 v187, v99, v179
	v_fmac_f32_e32 v184, v64, v180
	v_fmac_f32_e32 v185, v65, v181
	v_fmac_f32_e32 v186, v66, v182
	v_fmac_f32_e32 v187, v67, v183
	v_cmp_eq_u32_e32 vcc, 5, v63
	ds_read_b128 v[196:199], v62 offset:272
	ds_read_b128 v[220:223], v62 offset:288
	ds_read_b128 v[76:79], v62 offset:304
	v_add_f32_e32 v184, v184, v185
	v_add_f32_e32 v186, v186, v187
	v_add_f32_e32 v174, v184, v186
	s_waitcnt lgkmcnt(3)
	v_cndmask_b32_e64 v184, 0, 1.0, vcc
	v_mul_f32_e32 v186, v162, v174
	v_mul_f32_e32 v187, v163, v175
	v_fmac_f32_e32 v184, v188, v176
	v_mul_f32_e32 v185, v189, v177
	v_fmac_f32_e32 v186, v190, v178
	v_fmac_f32_e32 v187, v191, v179
	v_fmac_f32_e32 v184, v192, v180
	v_fmac_f32_e32 v185, v193, v181
	v_fmac_f32_e32 v186, v194, v182
	v_fmac_f32_e32 v187, v195, v183
	v_cmp_eq_u32_e32 vcc, 4, v63
	ds_read_b128 v[96:99], v62 offset:208
	ds_read_b128 v[64:67], v62 offset:224
	ds_read_b128 v[160:163], v62 offset:240
	v_add_f32_e32 v184, v184, v185
	v_add_f32_e32 v186, v186, v187
	v_add_f32_e32 v173, v184, v186
	s_waitcnt lgkmcnt(3)
	v_cndmask_b32_e64 v184, 0, 1.0, vcc
	v_mul_f32_e32 v185, v197, v173
	v_mul_f32_e32 v186, v198, v174
	v_mul_f32_e32 v187, v199, v175
	v_fmac_f32_e32 v184, v220, v176
	v_fmac_f32_e32 v185, v221, v177
	v_fmac_f32_e32 v186, v222, v178
	v_fmac_f32_e32 v187, v223, v179
	v_fmac_f32_e32 v184, v76, v180
	v_fmac_f32_e32 v185, v77, v181
	v_fmac_f32_e32 v186, v78, v182
	v_fmac_f32_e32 v187, v79, v183
	v_cmp_eq_u32_e32 vcc, 3, v63
	ds_read_b128 v[188:191], v62 offset:128
	ds_read_b128 v[192:195], v62 offset:144
	ds_read_b128 v[196:199], v62 offset:160
	ds_read_b128 v[220:223], v62 offset:176
	v_add_f32_e32 v184, v184, v185
	v_add_f32_e32 v186, v186, v187
	v_add_f32_e32 v172, v184, v186
	s_waitcnt lgkmcnt(4)
	v_cndmask_b32_e64 v184, 0, 1.0, vcc
	v_fmac_f32_e32 v184, v96, v172
	v_mul_f32_e32 v185, v97, v173
	v_mul_f32_e32 v186, v98, v174
	v_mul_f32_e32 v187, v99, v175
	v_fmac_f32_e32 v184, v64, v176
	v_fmac_f32_e32 v185, v65, v177
	v_fmac_f32_e32 v186, v66, v178
	v_fmac_f32_e32 v187, v67, v179
	v_fmac_f32_e32 v184, v160, v180
	v_fmac_f32_e32 v185, v161, v181
	v_fmac_f32_e32 v186, v162, v182
	v_fmac_f32_e32 v187, v163, v183
	v_cmp_eq_u32_e32 vcc, 2, v63
	ds_read_b128 v[76:79], v62 offset:64
	ds_read_b128 v[96:99], v62 offset:80
	ds_read_b128 v[64:67], v62 offset:96
	ds_read_b128 v[160:163], v62 offset:112
	v_add_f32_e32 v184, v184, v185
	v_add_f32_e32 v186, v186, v187
	v_add_f32_e32 v171, v184, v186
	s_waitcnt lgkmcnt(4)
	v_cndmask_b32_e64 v184, 0, 1.0, vcc
	v_mul_f32_e32 v187, v191, v171
	v_fmac_f32_e32 v184, v192, v172
	v_mul_f32_e32 v185, v193, v173
	v_mul_f32_e32 v186, v194, v174
	v_fmac_f32_e32 v187, v195, v175
	v_fmac_f32_e32 v184, v196, v176
	v_fmac_f32_e32 v185, v197, v177
	v_fmac_f32_e32 v186, v198, v178
	v_fmac_f32_e32 v187, v199, v179
	v_fmac_f32_e32 v184, v220, v180
	v_fmac_f32_e32 v185, v221, v181
	v_fmac_f32_e32 v186, v222, v182
	v_fmac_f32_e32 v187, v223, v183
	v_cmp_eq_u32_e32 vcc, 1, v63
	ds_read_b128 v[188:191], v62 offset:0
	ds_read_b128 v[192:195], v62 offset:16
	ds_read_b128 v[196:199], v62 offset:32
	ds_read_b128 v[220:223], v62 offset:48
	v_add_f32_e32 v184, v184, v185
	v_add_f32_e32 v186, v186, v187
	v_add_f32_e32 v170, v184, v186
	s_waitcnt lgkmcnt(4)
	v_cndmask_b32_e64 v184, 0, 1.0, vcc
	v_mul_f32_e32 v186, v78, v170
	v_mul_f32_e32 v187, v79, v171
	v_fmac_f32_e32 v184, v96, v172
	v_mul_f32_e32 v185, v97, v173
	v_fmac_f32_e32 v186, v98, v174
	v_fmac_f32_e32 v187, v99, v175
	v_fmac_f32_e32 v184, v64, v176
	v_fmac_f32_e32 v185, v65, v177
	v_fmac_f32_e32 v186, v66, v178
	v_fmac_f32_e32 v187, v67, v179
	v_fmac_f32_e32 v184, v160, v180
	v_fmac_f32_e32 v185, v161, v181
	v_fmac_f32_e32 v186, v162, v182
	v_fmac_f32_e32 v187, v163, v183
	v_cmp_eq_u32_e32 vcc, 0, v63
	v_add_f32_e32 v184, v184, v185
	v_add_f32_e32 v186, v186, v187
	v_add_f32_e32 v169, v184, v186
	s_waitcnt lgkmcnt(0)
	v_cndmask_b32_e64 v184, 0, 1.0, vcc
	v_mul_f32_e32 v185, v189, v169
	v_mul_f32_e32 v186, v190, v170
	v_mul_f32_e32 v187, v191, v171
	v_fmac_f32_e32 v184, v192, v172
	v_fmac_f32_e32 v185, v193, v173
	v_fmac_f32_e32 v186, v194, v174
	v_fmac_f32_e32 v187, v195, v175
	v_fmac_f32_e32 v184, v196, v176
	v_fmac_f32_e32 v185, v197, v177
	v_fmac_f32_e32 v186, v198, v178
	v_fmac_f32_e32 v187, v199, v179
	v_fmac_f32_e32 v184, v220, v180
	v_fmac_f32_e32 v185, v221, v181
	v_fmac_f32_e32 v186, v222, v182
	v_fmac_f32_e32 v187, v223, v183
	v_add_f32_e32 v184, v184, v185
	v_add_f32_e32 v186, v186, v187
	v_add_f32_e32 v168, v184, v186
	v_cvt_pk_f16_f32 v188, v168, v169
	v_cvt_pk_f16_f32 v189, v170, v171
	v_cvt_pk_f16_f32 v190, v176, v177
	v_cvt_pk_f16_f32 v191, v178, v179
	v_cvt_pk_f16_f32 v192, v172, v173
	v_cvt_pk_f16_f32 v193, v174, v175
	v_cvt_pk_f16_f32 v194, v180, v181
	v_cvt_pk_f16_f32 v195, v182, v183
	ds_write_b128 v68, v[188:191]
	ds_write_b128 v68, v[192:195] offset:16
